# work rebalancing: mlp_w_down[3] weight conversion moved from the 96 idle workgroups of MLA layer 1's down-projection phase to phase 0 (all 256 workgroups)
# baseline (speedup 1.0000x reference)
.LBB0_469:
	s_lshr_b32 s2, s31, 21
	s_mul_i32 s2, s2, s25
	s_sub_i32 s2, 0x800, s2
	s_sub_i32 s3, s2, s25
	s_cmp_ge_u32 s2, s25
	s_cselect_b32 s2, s3, s2
	s_sub_i32 s3, s2, s25
	s_cmp_ge_u32 s2, s25
	s_cselect_b32 s2, s3, s2
	s_sub_i32 s2, s19, s2
	s_ashr_i32 s3, s2, 31
	s_abs_i32 s2, s2
	s_mul_hi_u32 s4, s2, s31
	s_mul_i32 s4, s4, s25
	s_sub_i32 s2, s2, s4
	s_sub_i32 s4, s2, s25
	s_cmp_ge_u32 s2, s25
	s_cselect_b32 s2, s4, s2
	s_sub_i32 s4, s2, s25
	s_cmp_ge_u32 s2, s25
	s_cselect_b32 s2, s4, s2
	s_xor_b32 s2, s2, s3
	s_sub_i32 s2, s2, s3
	v_readlane_b32 s26, v255, 39
	v_readlane_b32 s30, v255, 35
	s_cmp_eq_u32 s24, s24
	v_readlane_b32 s27, v255, 40
	v_readlane_b32 s31, v255, 36
	s_cbranch_scc1 .LBB0_474
	v_lshrrev_b32_e32 v133, 3, v239
	v_and_b32_e32 v2, 31, v240
	v_and_b32_e32 v3, 4, v133
	v_and_b32_e32 v4, 7, v240
	v_lshlrev_b32_e32 v1, 2, v2
	v_lshl_add_u32 v6, v2, 7, s24
	v_bitop3_b32 v2, v3, v4, 1 bitop3:0x36
	v_lshlrev_b32_e32 v7, 4, v2
	v_bitop3_b32 v2, v3, v4, 2 bitop3:0x36
	v_lshlrev_b32_e32 v8, 4, v2
	v_bitop3_b32 v2, v133, v4, 3 bitop3:0x36
	v_bitop3_b32 v5, v133, v4, 4 bitop3:0x6c
	v_lshlrev_b32_e32 v4, 4, v2
	v_lshlrev_b32_e32 v2, 2, v239
	v_and_b32_e32 v9, 0x60, v2
	v_lshlrev_b32_e32 v2, 4, v239
	v_readlane_b32 s4, v252, 55
	v_and_b32_e32 v2, 0x70, v2
	v_mov_b32_e32 v3, v0
	v_readlane_b32 s5, v252, 56
	v_lshlrev_b32_e32 v5, 4, v5
	v_and_b32_e32 v132, 32, v240
	v_lshl_add_u64 v[130:131], s[4:5], 0, v[2:3]
	v_lshrrev_b32_e32 v2, 5, v239
	v_or_b32_e32 v3, v9, v2
	v_xor_b32_e32 v10, v2, v239
	v_or3_b32 v11, v2, 2, v9
	v_bitop3_b32 v12, v2, v239, 2 bitop3:0x36
	v_or3_b32 v13, v2, 4, v9
	v_bitop3_b32 v14, v2, v239, 4 bitop3:0x36
	v_or3_b32 v15, v2, 6, v9
	v_bitop3_b32 v16, v2, v239, 6 bitop3:0x36
	v_or3_b32 v18, v2, 10, v9
	v_bitop3_b32 v19, v2, v239, 10 bitop3:0x36
	v_or3_b32 v20, v2, 12, v9
	v_bitop3_b32 v21, v2, v239, 12 bitop3:0x36
	v_or3_b32 v22, v2, 14, v9
	v_bitop3_b32 v23, v2, v239, 14 bitop3:0x36
	v_or3_b32 v25, v2, 18, v9
	v_bitop3_b32 v26, v2, v239, 18 bitop3:0x36
	v_or3_b32 v27, v2, 20, v9
	v_bitop3_b32 v28, v2, v239, 20 bitop3:0x36
	v_or3_b32 v29, v2, 22, v9
	v_bitop3_b32 v30, v2, v239, 22 bitop3:0x36
	v_or3_b32 v32, v2, 26, v9
	v_bitop3_b32 v33, v2, v239, 26 bitop3:0x36
	v_or3_b32 v34, v2, 28, v9
	v_bitop3_b32 v35, v2, v239, 28 bitop3:0x36
	v_or3_b32 v9, v2, 30, v9
	v_bitop3_b32 v2, v2, v239, 30 bitop3:0x36
	v_lshlrev_b32_e32 v10, 4, v10
	v_lshl_add_u32 v3, v3, 7, s24
	v_lshlrev_b32_e32 v12, 4, v12
	v_lshlrev_b32_e32 v14, 4, v14
	v_lshlrev_b32_e32 v16, 4, v16
	v_lshlrev_b32_e32 v19, 4, v19
	v_lshlrev_b32_e32 v21, 4, v21
	v_lshlrev_b32_e32 v23, 4, v23
	v_lshlrev_b32_e32 v26, 4, v26
	v_lshlrev_b32_e32 v28, 4, v28
	v_lshlrev_b32_e32 v30, 4, v30
	v_lshlrev_b32_e32 v33, 4, v33
	v_lshlrev_b32_e32 v35, 4, v35
	v_lshlrev_b32_e32 v2, 4, v2
	v_and_b32_e32 v10, 0x70, v10
	v_and_b32_e32 v12, 0x70, v12
	v_lshl_add_u32 v11, v11, 7, s24
	v_and_b32_e32 v14, 0x70, v14
	v_lshl_add_u32 v13, v13, 7, s24
	v_and_b32_e32 v16, 0x70, v16
	v_lshl_add_u32 v15, v15, 7, s24
	v_add_u32_e32 v17, 0x400, v3
	v_and_b32_e32 v19, 0x70, v19
	v_lshl_add_u32 v18, v18, 7, s24
	v_and_b32_e32 v21, 0x70, v21
	v_lshl_add_u32 v20, v20, 7, s24
	v_and_b32_e32 v23, 0x70, v23
	v_lshl_add_u32 v22, v22, 7, s24
	v_add_u32_e32 v24, 0x800, v3
	v_and_b32_e32 v26, 0x70, v26
	v_lshl_add_u32 v25, v25, 7, s24
	v_and_b32_e32 v28, 0x70, v28
	v_lshl_add_u32 v27, v27, 7, s24
	v_and_b32_e32 v30, 0x70, v30
	v_lshl_add_u32 v29, v29, 7, s24
	v_add_u32_e32 v31, 0xc00, v3
	v_and_b32_e32 v33, 0x70, v33
	v_lshl_add_u32 v32, v32, 7, s24
	v_and_b32_e32 v35, 0x70, v35
	v_lshl_add_u32 v34, v34, 7, s24
	v_and_b32_e32 v2, 0x70, v2
	v_lshl_add_u32 v9, v9, 7, s24
	s_lshl_b32 s3, s2, 7
	s_lshl_b32 s14, s18, 7
	v_add_u32_e32 v134, v6, v5
	v_add_u32_e32 v135, v6, v7
	v_add_u32_e32 v136, v6, v8
	v_add_u32_e32 v137, v6, v4
	v_add_u32_e32 v138, v3, v10
	v_add_u32_e32 v139, v11, v12
	v_add_u32_e32 v140, v13, v14
	v_add_u32_e32 v141, v15, v16
	v_add_u32_e32 v142, v17, v10
	v_add_u32_e32 v143, v18, v19
	v_add_u32_e32 v144, v20, v21
	v_add_u32_e32 v145, v22, v23
	v_add_u32_e32 v146, v24, v10
	v_add_u32_e32 v147, v25, v26
	v_add_u32_e32 v148, v27, v28
	v_add_u32_e32 v149, v29, v30
	v_add_u32_e32 v150, v31, v10
	v_add_u32_e32 v151, v32, v33
	v_add_u32_e32 v152, v34, v35
	v_add_u32_e32 v153, v9, v2
	s_branch .LBB0_472

.LBB0_577:
	s_lshr_b32 s0, s14, 21
	s_mul_i32 s0, s0, s13
	s_sub_i32 s0, 0x800, s0
	s_sub_i32 s1, s0, s13
	s_cmp_ge_u32 s0, s13
	s_cselect_b32 s0, s1, s0
	s_sub_i32 s1, s0, s13
	s_cmp_ge_u32 s0, s13
	s_cselect_b32 s0, s1, s0
	s_sub_i32 s0, s19, s0
	s_ashr_i32 s1, s0, 31
	s_abs_i32 s0, s0
	s_mul_hi_u32 s2, s0, s14
	s_mul_i32 s2, s2, s13
	s_sub_i32 s0, s0, s2
	s_sub_i32 s2, s0, s13
	s_cmp_ge_u32 s0, s13
	s_cselect_b32 s0, s2, s0
	s_sub_i32 s2, s0, s13
	s_cmp_ge_u32 s0, s13
	s_cselect_b32 s0, s2, s0
	s_xor_b32 s0, s0, s1
	s_sub_i32 s2, s0, s1
	s_cmp_eq_u32 s24, s24
	s_cbranch_scc1 .LBB0_582
	v_lshrrev_b32_e32 v133, 3, v239
	v_and_b32_e32 v2, 31, v240
	v_and_b32_e32 v3, 4, v133
	v_and_b32_e32 v4, 7, v240
	v_lshlrev_b32_e32 v1, 2, v2
	v_lshl_add_u32 v6, v2, 7, s12
	v_bitop3_b32 v2, v3, v4, 1 bitop3:0x36
	v_lshlrev_b32_e32 v7, 4, v2
	v_bitop3_b32 v2, v3, v4, 2 bitop3:0x36
	v_lshlrev_b32_e32 v8, 4, v2
	v_bitop3_b32 v2, v133, v4, 3 bitop3:0x36
	v_bitop3_b32 v5, v133, v4, 4 bitop3:0x6c
	v_lshlrev_b32_e32 v4, 4, v2
	v_lshlrev_b32_e32 v2, 2, v239
	v_and_b32_e32 v9, 0x60, v2
	v_lshlrev_b32_e32 v2, 4, v239
	v_readlane_b32 s0, v252, 55
	v_and_b32_e32 v2, 0x70, v2
	v_mov_b32_e32 v3, v0
	v_readlane_b32 s1, v252, 56
	v_lshlrev_b32_e32 v5, 4, v5
	v_and_b32_e32 v132, 32, v240
	v_lshl_add_u64 v[130:131], s[0:1], 0, v[2:3]
	v_lshrrev_b32_e32 v2, 5, v239
	v_or_b32_e32 v3, v9, v2
	v_xor_b32_e32 v10, v2, v239
	v_or3_b32 v11, v2, 2, v9
	v_bitop3_b32 v12, v2, v239, 2 bitop3:0x36
	v_or3_b32 v13, v2, 4, v9
	v_bitop3_b32 v14, v2, v239, 4 bitop3:0x36
	v_or3_b32 v15, v2, 6, v9
	v_bitop3_b32 v16, v2, v239, 6 bitop3:0x36
	v_or3_b32 v18, v2, 10, v9
	v_bitop3_b32 v19, v2, v239, 10 bitop3:0x36
	v_or3_b32 v20, v2, 12, v9
	v_bitop3_b32 v21, v2, v239, 12 bitop3:0x36
	v_or3_b32 v22, v2, 14, v9
	v_bitop3_b32 v23, v2, v239, 14 bitop3:0x36
	v_or3_b32 v25, v2, 18, v9
	v_bitop3_b32 v26, v2, v239, 18 bitop3:0x36
	v_or3_b32 v27, v2, 20, v9
	v_bitop3_b32 v28, v2, v239, 20 bitop3:0x36
	v_or3_b32 v29, v2, 22, v9
	v_bitop3_b32 v30, v2, v239, 22 bitop3:0x36
	v_or3_b32 v32, v2, 26, v9
	v_bitop3_b32 v33, v2, v239, 26 bitop3:0x36
	v_or3_b32 v34, v2, 28, v9
	v_bitop3_b32 v35, v2, v239, 28 bitop3:0x36
	v_or3_b32 v9, v2, 30, v9
	v_bitop3_b32 v2, v2, v239, 30 bitop3:0x36
	v_lshlrev_b32_e32 v10, 4, v10
	v_lshl_add_u32 v3, v3, 7, s12
	v_lshlrev_b32_e32 v12, 4, v12
	v_lshlrev_b32_e32 v14, 4, v14
	v_lshlrev_b32_e32 v16, 4, v16
	v_lshlrev_b32_e32 v19, 4, v19
	v_lshlrev_b32_e32 v21, 4, v21
	v_lshlrev_b32_e32 v23, 4, v23
	v_lshlrev_b32_e32 v26, 4, v26
	v_lshlrev_b32_e32 v28, 4, v28
	v_lshlrev_b32_e32 v30, 4, v30
	v_lshlrev_b32_e32 v33, 4, v33
	v_lshlrev_b32_e32 v35, 4, v35
	v_lshlrev_b32_e32 v2, 4, v2
	v_and_b32_e32 v10, 0x70, v10
	v_and_b32_e32 v12, 0x70, v12
	v_lshl_add_u32 v11, v11, 7, s12
	v_and_b32_e32 v14, 0x70, v14
	v_lshl_add_u32 v13, v13, 7, s12
	v_and_b32_e32 v16, 0x70, v16
	v_lshl_add_u32 v15, v15, 7, s12
	v_add_u32_e32 v17, 0x400, v3
	v_and_b32_e32 v19, 0x70, v19
	v_lshl_add_u32 v18, v18, 7, s12
	v_and_b32_e32 v21, 0x70, v21
	v_lshl_add_u32 v20, v20, 7, s12
	v_and_b32_e32 v23, 0x70, v23
	v_lshl_add_u32 v22, v22, 7, s12
	v_add_u32_e32 v24, 0x800, v3
	v_and_b32_e32 v26, 0x70, v26
	v_lshl_add_u32 v25, v25, 7, s12
	v_and_b32_e32 v28, 0x70, v28
	v_lshl_add_u32 v27, v27, 7, s12
	v_and_b32_e32 v30, 0x70, v30
	v_lshl_add_u32 v29, v29, 7, s12
	v_add_u32_e32 v31, 0xc00, v3
	v_and_b32_e32 v33, 0x70, v33
	v_lshl_add_u32 v32, v32, 7, s12
	v_and_b32_e32 v35, 0x70, v35
	v_lshl_add_u32 v34, v34, 7, s12
	v_and_b32_e32 v2, 0x70, v2
	v_lshl_add_u32 v9, v9, 7, s12
	s_lshl_b32 s3, s2, 7
	s_lshl_b32 s10, s18, 7
	v_add_u32_e32 v134, v6, v5
	v_add_u32_e32 v135, v6, v7
	v_add_u32_e32 v136, v6, v8
	v_add_u32_e32 v137, v6, v4
	v_add_u32_e32 v138, v3, v10
	v_add_u32_e32 v139, v11, v12
	v_add_u32_e32 v140, v13, v14
	v_add_u32_e32 v141, v15, v16
	v_add_u32_e32 v142, v17, v10
	v_add_u32_e32 v143, v18, v19
	v_add_u32_e32 v144, v20, v21
	v_add_u32_e32 v145, v22, v23
	v_add_u32_e32 v146, v24, v10
	v_add_u32_e32 v147, v25, v26
	v_add_u32_e32 v148, v27, v28
	v_add_u32_e32 v149, v29, v30
	v_add_u32_e32 v150, v31, v10
	v_add_u32_e32 v151, v32, v33
	v_add_u32_e32 v152, v34, v35
	v_add_u32_e32 v153, v9, v2
	s_branch .LBB0_580

.LBB0_669:
	s_addk_i32 s25, 0x1000
	s_add_i32 s24, s24, 1
	s_cmp_lg_u32 s24, 4
	s_cbranch_scc1 .LBB0_675
	s_branch .LBB0_684

.LBB0_675:
	s_lshl_b32 s2, s24, 26
	v_readlane_b32 s0, v252, 28
	s_add_u32 s0, s0, s2
	v_readlane_b32 s1, v252, 29
	s_addc_u32 s1, s1, 0
	s_cmp_eq_u32 s24, 3
	s_cbranch_scc0 .Lp0_mlp_normal
	s_mov_b32 s3, s25
	s_branch .LBB0_670
.Lp0_mlp_normal:
	s_abs_i32 s4, s25
	s_mul_hi_u32 s5, s4, s31
	s_mul_i32 s5, s5, s19
	s_sub_i32 s4, s4, s5
	s_ashr_i32 s3, s25, 31
	s_sub_i32 s5, s4, s19
	s_cmp_ge_u32 s4, s19
	s_cselect_b32 s4, s5, s4
	s_sub_i32 s5, s4, s19
	s_cmp_ge_u32 s4, s19
	s_cselect_b32 s4, s5, s4
	s_xor_b32 s4, s4, s3
	s_sub_i32 s3, s3, s4
	s_add_i32 s3, s18, s3
	s_ashr_i32 s4, s3, 31
	s_abs_i32 s3, s3
	s_mul_hi_u32 s5, s3, s31
	s_mul_i32 s5, s5, s19
	s_sub_i32 s3, s3, s5
	s_sub_i32 s5, s3, s19
	s_cmp_ge_u32 s3, s19
	s_cselect_b32 s3, s5, s3
	s_sub_i32 s5, s3, s19
	s_cmp_ge_u32 s3, s19
	s_cselect_b32 s3, s5, s3
	s_xor_b32 s3, s3, s4
	s_sub_i32 s3, s3, s4
	s_cmpk_gt_i32 s3, 0x7ff
	s_cbranch_scc1 .LBB0_682
	v_readlane_b32 s72, v252, 59
	v_readlane_b32 s74, v252, 61
	v_readlane_b32 s75, v252, 62
	s_add_u32 s10, s74, s2
	s_addc_u32 s11, s75, 0
	s_lshl_b32 s70, s24, 11
	v_readlane_b32 s52, v253, 27
	s_lshl_b64 s[4:5], s[70:71], 2
	v_readlane_b32 s66, v253, 41
	v_readlane_b32 s67, v253, 42
	s_add_u32 s28, s66, s4
	v_lshlrev_b32_e32 v2, 1, v162
	v_mov_b32_e32 v3, v0
	s_addc_u32 s29, s67, s5
	v_lshl_add_u64 v[164:165], s[0:1], 0, v[2:3]
	s_lshl_b32 s30, s3, 7
	s_lshl_b32 s45, s44, 7
	v_mov_b32_e32 v211, v163
	v_mov_b32_e32 v212, v167
	v_readlane_b32 s73, v252, 60
	v_readlane_b32 s76, v252, 63
	v_readlane_b32 s77, v253, 0
	v_readlane_b32 s78, v253, 1
	v_readlane_b32 s79, v253, 2
	v_readlane_b32 s53, v253, 28
	v_readlane_b32 s54, v253, 29
	v_readlane_b32 s55, v253, 30
	v_readlane_b32 s56, v253, 31
	v_readlane_b32 s57, v253, 32
	v_readlane_b32 s58, v253, 33
	v_readlane_b32 s59, v253, 34
	v_readlane_b32 s60, v253, 35
	v_readlane_b32 s61, v253, 36
	v_readlane_b32 s62, v253, 37
	v_readlane_b32 s63, v253, 38
	v_readlane_b32 s64, v253, 39
	v_readlane_b32 s65, v253, 40
	s_branch .LBB0_678

.LBB0_682:
	s_add_i32 s3, s25, 0x800
	s_cmp_eq_u32 s24, 2
	s_cbranch_scc0 .LBB0_670
	s_mov_b32 s25, s3
	s_add_i32 s24, s24, 1
	s_branch .LBB0_675
